# P3 sample rows: mini-GEMM+atomic hoisted to P3 start, counter after main loop, normalise/store at end; x-load ring 3 slots
# baseline (speedup 1.0000x reference)
.LBB0_479:
	s_and_b64 vcc, exec, s[0:1]
	s_cbranch_vccz .LBB0_531
	s_cmpk_gt_i32 s2, 0xff
	v_readfirstlane_b32 s33, v201
	s_cbranch_scc1 .LBB0_531
	s_lshl_b32 s0, s2, 1
	s_lshr_b32 s1, s79, 8
	s_add_i32 s32, s1, s0
	s_and_b32 s72, s32, 7
	s_waitcnt vmcnt(0)
	v_lshl_or_b32 v12, s72, 4, v233
	s_bfe_u32 s3, s79, 0x20006
	v_lshlrev_b32_e32 v8, 12, v12
	v_mov_b32_e32 v9, 0
	s_mov_b32 s1, 0
	s_waitcnt lgkmcnt(0)
	v_lshl_add_u64 v[0:1], s[12:13], 0, v[8:9]
	s_lshl_b32 s0, s3, 10
	s_lshl_b32 s32, s32, 1
	v_lshl_add_u64 v[0:1], v[0:1], 0, s[0:1]
	v_lshlrev_b32_e32 v2, 4, v232
	v_mov_b32_e32 v3, v9
	s_and_b32 s32, s32, -16
	v_lshl_add_u64 v[10:11], v[0:1], 0, v[2:3]
	v_or_b32_e32 v0, s32, v233
	v_ashrrev_i32_e32 v1, 31, v0
	v_lshlrev_b64 v[0:1], 12, v[0:1]
	v_lshl_add_u64 v[0:1], s[88:89], 0, v[0:1]
	v_lshl_add_u64 v[0:1], v[0:1], 0, s[0:1]
	v_lshl_add_u64 v[74:75], v[0:1], 0, v[2:3]
	global_load_dwordx4 v[0:3], v[74:75], off
	s_brev_b32 s0, 32
	v_add_co_u32_e32 v18, vcc, s0, v10
	s_mov_b64 s[0:1], 0x4000000
	s_nop 0
	v_addc_co_u32_e32 v19, vcc, 0, v11, vcc
	global_load_dwordx4 v[4:7], v[18:19], off
	global_load_dwordx4 v[14:17], v[74:75], off offset:64
	v_lshl_add_u64 v[10:11], v[10:11], 0, s[0:1]
	global_load_dwordx4 v[18:21], v[74:75], off offset:128
	global_load_dwordx4 v[22:25], v[10:11], off offset:64
	global_load_dwordx4 v[26:29], v[10:11], off offset:128
	global_load_dwordx4 v[30:33], v[74:75], off offset:192
	global_load_dwordx4 v[34:37], v[74:75], off offset:256
	global_load_dwordx4 v[38:41], v[10:11], off offset:192
	global_load_dwordx4 v[42:45], v[10:11], off offset:256
	global_load_dwordx4 v[46:49], v[74:75], off offset:320
	global_load_dwordx4 v[50:53], v[10:11], off offset:320
	global_load_dwordx4 v[54:57], v[10:11], off offset:384
	global_load_dwordx4 v[58:61], v[74:75], off offset:384
	global_load_dwordx4 v[62:65], v[10:11], off offset:960
	global_load_dwordx4 v[66:69], v[74:75], off offset:960
	s_and_b32 s0, s79, 0xfffffc0
	s_lshl_b32 s0, s0, 4
	s_add_i32 s0, s0, 0x20800
	s_cmp_lg_u32 s3, 0
	s_waitcnt vmcnt(11)
	v_mfma_f32_16x16x32_bf16 v[14:17], v[14:17], v[22:25], 0
	v_mfma_f32_16x16x32_bf16 v[0:3], v[0:3], v[4:7], 0
	global_load_dwordx4 v[4:7], v[74:75], off offset:448
	global_load_dwordx4 v[70:73], v[10:11], off offset:448
	global_load_dwordx4 v[22:25], v[74:75], off offset:512
	s_waitcnt vmcnt(13)
	v_mfma_f32_16x16x32_bf16 v[0:3], v[18:21], v[26:29], v[0:3]
	global_load_dwordx4 v[18:21], v[10:11], off offset:512
	s_waitcnt vmcnt(11)
	v_mfma_f32_16x16x32_bf16 v[14:17], v[30:33], v[38:41], v[14:17]
	global_load_dwordx4 v[26:29], v[74:75], off offset:576
	global_load_dwordx4 v[30:33], v[74:75], off offset:640
	s_waitcnt vmcnt(12)
	v_mfma_f32_16x16x32_bf16 v[0:3], v[34:37], v[42:45], v[0:3]
	global_load_dwordx4 v[34:37], v[10:11], off offset:576
	global_load_dwordx4 v[38:41], v[10:11], off offset:640
	s_waitcnt vmcnt(12)
	v_mfma_f32_16x16x32_bf16 v[14:17], v[46:49], v[50:53], v[14:17]
	global_load_dwordx4 v[42:45], v[74:75], off offset:704
	global_load_dwordx4 v[46:49], v[74:75], off offset:768
	s_waitcnt vmcnt(12)
	v_mfma_f32_16x16x32_bf16 v[0:3], v[58:61], v[54:57], v[0:3]
	global_load_dwordx4 v[50:53], v[10:11], off offset:704
	global_load_dwordx4 v[54:57], v[10:11], off offset:768
	s_waitcnt vmcnt(10)
	v_mfma_f32_16x16x32_bf16 v[4:7], v[4:7], v[70:73], v[14:17]
	s_nop 2
	global_load_dwordx4 v[14:17], v[74:75], off offset:832
	s_waitcnt vmcnt(9)
	v_mfma_f32_16x16x32_bf16 v[0:3], v[22:25], v[18:21], v[0:3]
	global_load_dwordx4 v[18:21], v[10:11], off offset:832
	global_load_dwordx4 v[22:25], v[74:75], off offset:896
	s_waitcnt vmcnt(8)
	v_mfma_f32_16x16x32_bf16 v[4:7], v[26:29], v[34:37], v[4:7]
	global_load_dwordx4 v[26:29], v[10:11], off offset:896
	v_lshl_or_b32 v10, v232, 2, s32
	v_ashrrev_i32_e32 v11, 31, v10
	s_waitcnt vmcnt(8)
	v_mfma_f32_16x16x32_bf16 v[0:3], v[30:33], v[38:41], v[0:3]
	s_waitcnt vmcnt(5)
	v_mfma_f32_16x16x32_bf16 v[30:33], v[42:45], v[50:53], v[4:7]
	s_nop 2
	v_lshl_add_u64 v[4:5], s[46:47], 0, v[8:9]
	v_lshlrev_b64 v[6:7], 2, v[10:11]
	s_waitcnt vmcnt(4)
	v_mfma_f32_16x16x32_bf16 v[34:37], v[46:49], v[54:57], v[0:3]
	v_lshl_add_u32 v9, v200, 4, s0
	s_nop 1
	v_lshl_add_u64 v[0:1], v[4:5], 0, v[6:7]
	v_lshl_add_u64 v[2:3], s[64:65], 0, v[6:7]
	global_load_dwordx4 v[4:7], v[0:1], off
	s_waitcnt vmcnt(3)
	v_mfma_f32_16x16x32_bf16 v[14:17], v[14:17], v[18:21], v[30:33]
	global_load_dwordx4 v[0:3], v[2:3], off
	s_waitcnt vmcnt(2)
	v_mfma_f32_16x16x32_bf16 v[18:21], v[22:25], v[26:29], v[34:37]
	v_mfma_f32_16x16x32_bf16 v[14:17], v[66:69], v[62:65], v[14:17]
	s_nop 7
	v_pk_add_f32 v[16:17], v[20:21], v[16:17]
	v_pk_add_f32 v[14:15], v[18:19], v[14:15]
	ds_write_b128 v9, v[14:17]
	s_waitcnt lgkmcnt(0)
	s_barrier
	s_waitcnt vmcnt(0)
	s_cbranch_scc1 .Ls1_done
	s_and_b32 s0, s79, 0xfffff80
	ds_read_b128 v[14:17], v9
	s_lshl_b32 s0, s0, 4
	s_add_i32 s0, s0, 0x20800
	v_lshlrev_b32_e32 v9, 4, v200
	v_add_u32_e32 v13, s0, v9
	s_and_b32 s0, s79, 0xfffff40
	s_lshl_b32 s0, s0, 4
	s_add_i32 s0, s0, 0x20800
	s_waitcnt vmcnt(1) lgkmcnt(0)
	v_pk_add_f32 v[24:25], v[4:5], v[14:15]
	v_add_u32_e32 v4, s0, v9
	s_and_b32 s0, s79, 0xfffff00
	s_lshl_b32 s0, s0, 4
	ds_read_b128 v[18:21], v13 offset:1024
	s_add_i32 s0, s0, 0x20800
	v_pk_add_f32 v[22:23], v[6:7], v[16:17]
	ds_read_b128 v[4:7], v4 offset:2048
	v_add_u32_e32 v9, s0, v9
	ds_read_b128 v[14:17], v9 offset:3072
	s_waitcnt lgkmcnt(2)
	v_pk_add_f32 v[20:21], v[22:23], v[20:21]
	v_pk_add_f32 v[18:19], v[24:25], v[18:19]
	s_waitcnt lgkmcnt(1)
	v_pk_add_f32 v[6:7], v[20:21], v[6:7]
	v_pk_add_f32 v[18:19], v[18:19], v[4:5]
	s_waitcnt lgkmcnt(0)
	v_pk_add_f32 v[4:5], v[6:7], v[16:17]
	v_pk_add_f32 v[6:7], v[18:19], v[14:15]
	v_mul_f32_e32 v13, v5, v5
	v_mul_f32_e32 v9, v7, v7
	v_fmac_f32_e32 v9, v6, v6
	v_fmac_f32_e32 v13, v4, v4
	v_add_f32_e32 v9, v9, v13
	v_mbcnt_lo_u32_b32 v13, -1, 0
	v_mbcnt_hi_u32_b32 v13, -1, v13
	v_and_b32_e32 v15, 64, v13
	v_xor_b32_e32 v14, 16, v13
	v_add_u32_e32 v15, 64, v15
	v_cmp_lt_i32_e32 vcc, v14, v15
	v_lshlrev_b32_e32 v12, 2, v12
	s_nop 0
	v_cndmask_b32_e32 v14, v13, v14, vcc
	v_lshlrev_b32_e32 v14, 2, v14
	ds_bpermute_b32 v14, v14, v9
	s_waitcnt lgkmcnt(0)
	v_add_f32_e32 v9, v9, v14
	v_xor_b32_e32 v14, 32, v13
	v_cmp_lt_i32_e32 vcc, v14, v15
	s_nop 1
	v_cndmask_b32_e32 v13, v13, v14, vcc
	v_lshlrev_b32_e32 v13, 2, v13
	ds_bpermute_b32 v14, v13, v9
	s_waitcnt vmcnt(0)
	v_mov_b32_e32 v242, v0
	v_mov_b32_e32 v243, v1
	v_mov_b32_e32 v244, v2
	v_mov_b32_e32 v245, v3
	v_mov_b32_e32 v246, v4
	v_mov_b32_e32 v247, v5
	v_mov_b32_e32 v248, v6
	v_mov_b32_e32 v249, v7
	v_mov_b32_e32 v250, v8
	v_mov_b32_e32 v251, v10
	v_mov_b32_e32 v252, v12
	v_cmp_gt_u32_e32 vcc, 16, v200
	s_and_saveexec_b64 s[0:1], vcc
	s_cbranch_execz .Ls1_544
	v_mov_b32_e32 v13, 0
	v_lshl_add_u64 v[16:17], s[68:69], 0, v[12:13]
	s_waitcnt lgkmcnt(0)
	v_add_f32_e32 v9, v9, v14
	v_add_co_u32_e32 v14, vcc, 0x20000, v16
	s_nop 1
	v_addc_co_u32_e32 v15, vcc, 0, v17, vcc
	global_atomic_add_f32 v[14:15], v9, off offset:1024

.Ls1_done:
	s_ashr_i32 s38, s2, 31
	s_lshr_b32 s0, s38, 29
	s_add_i32 s4, s2, s0
	s_and_b32 s0, s4, -8
	s_sub_i32 s5, s2, s0
	s_cmp_gt_i32 s5, -1
	s_cbranch_scc0 .LBB0_483
	s_lshl_b32 s3, s5, 5
	s_cbranch_execz .LBB0_484
	s_branch .LBB0_485

.LBB0_500:
	s_waitcnt vmcnt(0)
	s_bfe_u32 s0, s79, 0x20006
	s_cmp_lg_u32 s0, 0
	s_cbranch_scc1 .Ls2_done
	s_lshl_b32 s0, s72, 8
	s_add_u32 s0, s68, s0
	s_addc_u32 s1, s69, 0
	v_mov_b32_e32 v190, 0x48000
	v_mov_b32_e32 v191, 1
	s_mov_b64 s[80:81], exec
	s_mov_b64 exec, 1
	s_nop 1
	global_atomic_add v190, v191, s[0:1]
	s_mov_b64 exec, s[80:81]
.Ls2_done:
	s_cmpk_gt_u32 s33, 0xff
	s_cbranch_scc1 .LBB0_502
	s_barrier
.LBB0_502:
	s_lshl_b32 s0, s14, 8
	s_add_i32 s4, s0, s15
	s_lshl_b32 s1, s3, 5
	v_or_b32_e32 v130, s4, v233
	s_lshl_b32 s4, s51, 8
	s_or_b32 s1, s4, s1
	v_ashrrev_i32_e32 v131, 31, v130
	v_lshl_or_b32 v128, v144, 2, s1
	v_lshlrev_b64 v[132:133], 12, v[130:131]
	v_ashrrev_i32_e32 v129, 31, v128
	v_lshl_add_u64 v[134:135], s[44:45], 0, v[132:133]
	v_lshl_add_u64 v[142:143], v[128:129], 2, v[134:135]
	s_barrier
	v_lshl_add_u32 v198, v128, 2, v132
	global_load_dwordx4 v[182:185], v198, s[44:45] nt
	global_load_dwordx4 v[186:189], v198, s[44:45] offset:64 nt
	global_load_dwordx4 v[190:193], v198, s[44:45] offset:512 nt
	global_load_dwordx4 v[194:197], v198, s[44:45] offset:576 nt
	v_add_u32_e32 v199, 0x10000, v198
	global_load_dwordx4 v[202:205], v199, s[44:45] nt
	global_load_dwordx4 v[206:209], v199, s[44:45] offset:64 nt
	global_load_dwordx4 v[210:213], v199, s[44:45] offset:512 nt
	global_load_dwordx4 v[214:217], v199, s[44:45] offset:576 nt
	v_add_u32_e32 v199, 0x20000, v198
	global_load_dwordx4 v[218:221], v199, s[44:45] nt
	global_load_dwordx4 v[222:225], v199, s[44:45] offset:64 nt
	global_load_dwordx4 v[234:237], v199, s[44:45] offset:512 nt
	global_load_dwordx4 v[238:241], v199, s[44:45] offset:576 nt
	v_mbcnt_lo_u32_b32 v142, -1, 0
	v_mbcnt_hi_u32_b32 v142, -1, v142
	v_and_b32_e32 v145, 64, v142
	v_xor_b32_e32 v143, 16, v142
	v_add_u32_e32 v145, 64, v145
	v_cmp_lt_i32_e32 vcc, v143, v145
	v_xor_b32_e32 v154, 32, v142
	s_lshl_b32 s1, s15, 2
	v_cndmask_b32_e32 v143, v142, v143, vcc
	v_lshlrev_b32_e32 v171, 2, v143
	v_cmp_lt_i32_e32 vcc, v154, v145
	s_add_i32 s1, s1, 0
	s_lshl_b32 s3, s3, 10
	s_add_i32 s1, s1, s3
	v_lshl_add_u32 v173, v233, 2, s1
	s_waitcnt vmcnt(8)
	v_pk_add_f32 v[126:127], v[126:127], v[184:185]
	v_pk_add_f32 v[124:125], v[124:125], v[182:183]
	v_pk_add_f32 v[122:123], v[122:123], v[188:189]
	v_pk_add_f32 v[120:121], v[120:121], v[186:187]
	v_pk_add_f32 v[118:119], v[118:119], v[192:193]
	v_pk_add_f32 v[116:117], v[116:117], v[190:191]
	v_mul_f32_e32 v134, v125, v125
	v_mul_f32_e32 v135, v127, v127
	v_mul_f32_e32 v136, v121, v121
	v_mul_f32_e32 v137, v123, v123
	v_pk_add_f32 v[114:115], v[114:115], v[196:197]
	v_pk_add_f32 v[112:113], v[112:113], v[194:195]
	v_add_u32_e32 v199, 0x30000, v198
	global_load_dwordx4 v[182:185], v199, s[44:45] nt
	global_load_dwordx4 v[186:189], v199, s[44:45] offset:64 nt
	global_load_dwordx4 v[190:193], v199, s[44:45] offset:512 nt
	global_load_dwordx4 v[194:197], v199, s[44:45] offset:576 nt
	v_mul_f32_e32 v138, v117, v117
	v_mul_f32_e32 v139, v119, v119
	v_fmac_f32_e32 v134, v124, v124
	v_fmac_f32_e32 v135, v126, v126
	v_fmac_f32_e32 v136, v120, v120
	v_fmac_f32_e32 v137, v122, v122
	v_mul_f32_e32 v140, v113, v113
	v_mul_f32_e32 v141, v115, v115
	v_fmac_f32_e32 v138, v116, v116
	v_fmac_f32_e32 v139, v118, v118
	v_add_f32_e32 v134, v134, v135
	v_add_f32_e32 v135, v136, v137
	v_fmac_f32_e32 v140, v112, v112
	v_fmac_f32_e32 v141, v114, v114
	v_add_f32_e32 v136, v138, v139
	v_add_f32_e32 v134, v134, v135
	v_add_f32_e32 v137, v140, v141
	v_add_f32_e32 v134, v134, v136
	v_add_f32_e32 v134, v134, v137
	ds_bpermute_b32 v135, v171, v134
	v_cndmask_b32_e32 v136, v142, v154, vcc
	v_lshlrev_b32_e32 v172, 2, v136
	v_cmp_eq_u32_e32 vcc, 0, v144
	s_waitcnt lgkmcnt(0)
	v_add_f32_e32 v134, v134, v135
	ds_bpermute_b32 v135, v172, v134
	s_and_saveexec_b64 s[4:5], vcc
	s_cbranch_execz .LBB0_504
	s_waitcnt lgkmcnt(0)
	v_add_f32_e32 v134, v134, v135
	ds_write_b32 v173, v134
.LBB0_504:
	s_or_b64 exec, exec, s[4:5]
	v_or_b32_e32 v136, 16, v130
	v_ashrrev_i32_e32 v137, 31, v136
	s_waitcnt lgkmcnt(0)
	v_lshlrev_b64 v[134:135], 12, v[136:137]
	v_lshl_add_u64 v[138:139], s[44:45], 0, v[134:135]
	v_lshl_add_u64 v[150:151], v[128:129], 2, v[138:139]
	s_nop 0
	s_waitcnt vmcnt(11)
	v_pk_add_f32 v[110:111], v[110:111], v[204:205]
	v_pk_add_f32 v[108:109], v[108:109], v[202:203]
	s_waitcnt vmcnt(10)
	v_pk_add_f32 v[106:107], v[106:107], v[208:209]
	v_pk_add_f32 v[104:105], v[104:105], v[206:207]
	s_waitcnt vmcnt(9)
	v_pk_add_f32 v[102:103], v[102:103], v[212:213]
	v_pk_add_f32 v[100:101], v[100:101], v[210:211]
	v_mul_f32_e32 v138, v109, v109
	v_mul_f32_e32 v139, v111, v111
	v_mul_f32_e32 v140, v105, v105
	v_mul_f32_e32 v141, v107, v107
	s_waitcnt vmcnt(8)
	v_pk_add_f32 v[98:99], v[98:99], v[216:217]
	v_pk_add_f32 v[96:97], v[96:97], v[214:215]
	v_add_u32_e32 v199, 0x80000, v198
	global_load_dwordx4 v[202:205], v199, s[44:45] nt
	global_load_dwordx4 v[206:209], v199, s[44:45] offset:64 nt
	global_load_dwordx4 v[210:213], v199, s[44:45] offset:512 nt
	global_load_dwordx4 v[214:217], v199, s[44:45] offset:576 nt
	v_mul_f32_e32 v142, v101, v101
	v_mul_f32_e32 v143, v103, v103
	v_fmac_f32_e32 v138, v108, v108
	v_fmac_f32_e32 v139, v110, v110
	v_fmac_f32_e32 v140, v104, v104
	v_fmac_f32_e32 v141, v106, v106
	v_mul_f32_e32 v144, v97, v97
	v_mul_f32_e32 v145, v99, v99
	v_fmac_f32_e32 v142, v100, v100
	v_fmac_f32_e32 v143, v102, v102
	v_add_f32_e32 v138, v138, v139
	v_add_f32_e32 v139, v140, v141
	v_fmac_f32_e32 v144, v96, v96
	v_fmac_f32_e32 v145, v98, v98
	v_add_f32_e32 v140, v142, v143
	v_add_f32_e32 v138, v138, v139
	v_add_f32_e32 v138, v138, v140
	v_add_f32_e32 v139, v144, v145
	v_add_f32_e32 v138, v138, v139
	ds_bpermute_b32 v139, v171, v138
	s_waitcnt lgkmcnt(0)
	v_add_f32_e32 v138, v138, v139
	ds_bpermute_b32 v139, v172, v138
	s_and_saveexec_b64 s[4:5], vcc
	s_cbranch_execz .LBB0_506
	s_waitcnt lgkmcnt(0)
	v_add_f32_e32 v138, v138, v139
	ds_write_b32 v173, v138 offset:64
.LBB0_506:
	s_or_b64 exec, exec, s[4:5]
	v_or_b32_e32 v140, 32, v130
	v_ashrrev_i32_e32 v141, 31, v140
	s_waitcnt lgkmcnt(0)
	v_lshlrev_b64 v[138:139], 12, v[140:141]
	v_lshl_add_u64 v[142:143], s[44:45], 0, v[138:139]
	v_lshl_add_u64 v[154:155], v[128:129], 2, v[142:143]
	s_nop 0
	s_waitcnt vmcnt(11)
	v_pk_add_f32 v[94:95], v[94:95], v[220:221]
	v_pk_add_f32 v[92:93], v[92:93], v[218:219]
	s_waitcnt vmcnt(10)
	v_pk_add_f32 v[90:91], v[90:91], v[224:225]
	v_pk_add_f32 v[88:89], v[88:89], v[222:223]
	s_waitcnt vmcnt(9)
	v_pk_add_f32 v[86:87], v[86:87], v[236:237]
	v_pk_add_f32 v[84:85], v[84:85], v[234:235]
	v_mul_f32_e32 v142, v93, v93
	v_mul_f32_e32 v143, v95, v95
	v_mul_f32_e32 v144, v89, v89
	v_mul_f32_e32 v145, v91, v91
	s_waitcnt vmcnt(8)
	v_pk_add_f32 v[82:83], v[82:83], v[240:241]
	v_pk_add_f32 v[80:81], v[80:81], v[238:239]
	v_add_u32_e32 v199, 0x90000, v198
	global_load_dwordx4 v[218:221], v199, s[44:45] nt
	global_load_dwordx4 v[222:225], v199, s[44:45] offset:64 nt
	global_load_dwordx4 v[234:237], v199, s[44:45] offset:512 nt
	global_load_dwordx4 v[238:241], v199, s[44:45] offset:576 nt
	v_mul_f32_e32 v146, v85, v85
	v_mul_f32_e32 v147, v87, v87
	v_fmac_f32_e32 v142, v92, v92
	v_fmac_f32_e32 v143, v94, v94
	v_fmac_f32_e32 v144, v88, v88
	v_fmac_f32_e32 v145, v90, v90
	v_mul_f32_e32 v148, v81, v81
	v_mul_f32_e32 v149, v83, v83
	v_fmac_f32_e32 v146, v84, v84
	v_fmac_f32_e32 v147, v86, v86
	v_add_f32_e32 v142, v142, v143
	v_add_f32_e32 v143, v144, v145
	v_fmac_f32_e32 v148, v80, v80
	v_fmac_f32_e32 v149, v82, v82
	v_add_f32_e32 v144, v146, v147
	v_add_f32_e32 v142, v142, v143
	v_add_f32_e32 v142, v142, v144
	v_add_f32_e32 v143, v148, v149
	v_add_f32_e32 v142, v142, v143
	ds_bpermute_b32 v143, v171, v142
	s_waitcnt lgkmcnt(0)
	v_add_f32_e32 v142, v142, v143
	ds_bpermute_b32 v143, v172, v142
	s_and_saveexec_b64 s[4:5], vcc
	s_cbranch_execz .LBB0_508
	s_waitcnt lgkmcnt(0)
	v_add_f32_e32 v142, v142, v143
	ds_write_b32 v173, v142 offset:128
.LBB0_508:
	s_or_b64 exec, exec, s[4:5]
	v_or_b32_e32 v144, 48, v130
	v_ashrrev_i32_e32 v145, 31, v144
	s_waitcnt lgkmcnt(0)
	v_lshlrev_b64 v[142:143], 12, v[144:145]
	v_lshl_add_u64 v[146:147], s[44:45], 0, v[142:143]
	v_lshl_add_u64 v[158:159], v[128:129], 2, v[146:147]
	s_nop 0
	s_waitcnt vmcnt(11)
	v_pk_add_f32 v[78:79], v[78:79], v[184:185]
	v_pk_add_f32 v[146:147], v[76:77], v[182:183]
	s_waitcnt vmcnt(10)
	v_pk_add_f32 v[74:75], v[74:75], v[188:189]
	v_pk_add_f32 v[76:77], v[72:73], v[186:187]
	s_waitcnt vmcnt(9)
	v_pk_add_f32 v[70:71], v[70:71], v[192:193]
	v_pk_add_f32 v[68:69], v[68:69], v[190:191]
	v_mul_f32_e32 v72, v147, v147
	v_mul_f32_e32 v73, v79, v79
	v_mul_f32_e32 v148, v77, v77
	v_mul_f32_e32 v149, v75, v75
	s_waitcnt vmcnt(8)
	v_pk_add_f32 v[66:67], v[66:67], v[196:197]
	v_pk_add_f32 v[64:65], v[64:65], v[194:195]
	v_add_u32_e32 v199, 0xa0000, v198
	global_load_dwordx4 v[182:185], v199, s[44:45] nt
	global_load_dwordx4 v[186:189], v199, s[44:45] offset:64 nt
	global_load_dwordx4 v[190:193], v199, s[44:45] offset:512 nt
	global_load_dwordx4 v[194:197], v199, s[44:45] offset:576 nt
	v_mul_f32_e32 v150, v69, v69
	v_mul_f32_e32 v151, v71, v71
	v_fmac_f32_e32 v72, v146, v146
	v_fmac_f32_e32 v73, v78, v78
	v_fmac_f32_e32 v148, v76, v76
	v_fmac_f32_e32 v149, v74, v74
	v_mul_f32_e32 v152, v65, v65
	v_mul_f32_e32 v153, v67, v67
	v_fmac_f32_e32 v150, v68, v68
	v_fmac_f32_e32 v151, v70, v70
	v_add_f32_e32 v72, v72, v73
	v_add_f32_e32 v73, v148, v149
	v_fmac_f32_e32 v152, v64, v64
	v_fmac_f32_e32 v153, v66, v66
	v_add_f32_e32 v148, v150, v151
	v_add_f32_e32 v72, v72, v73
	v_add_f32_e32 v72, v72, v148
	v_add_f32_e32 v73, v152, v153
	v_add_f32_e32 v72, v72, v73
	ds_bpermute_b32 v73, v171, v72
	s_waitcnt lgkmcnt(0)
	v_add_f32_e32 v72, v72, v73
	ds_bpermute_b32 v73, v172, v72
	s_and_saveexec_b64 s[4:5], vcc
	s_cbranch_execz .LBB0_510
	s_waitcnt lgkmcnt(0)
	v_add_f32_e32 v72, v72, v73
	ds_write_b32 v173, v72 offset:192
.LBB0_510:
	s_or_b64 exec, exec, s[4:5]
	s_mov_b64 s[4:5], 0x80000
	s_waitcnt lgkmcnt(0)
	v_lshl_add_u64 v[72:73], v[132:133], 0, s[4:5]
	v_lshl_add_u64 v[148:149], s[44:45], 0, v[72:73]
	v_lshl_add_u64 v[160:161], v[128:129], 2, v[148:149]
	s_nop 0
	s_waitcnt vmcnt(11)
	v_pk_add_f32 v[62:63], v[62:63], v[204:205]
	v_pk_add_f32 v[148:149], v[60:61], v[202:203]
	s_waitcnt vmcnt(10)
	v_pk_add_f32 v[58:59], v[58:59], v[208:209]
	v_pk_add_f32 v[60:61], v[56:57], v[206:207]
	s_waitcnt vmcnt(9)
	v_pk_add_f32 v[54:55], v[54:55], v[212:213]
	v_pk_add_f32 v[52:53], v[52:53], v[210:211]
	v_mul_f32_e32 v56, v149, v149
	v_mul_f32_e32 v57, v63, v63
	v_mul_f32_e32 v150, v61, v61
	v_mul_f32_e32 v151, v59, v59
	s_waitcnt vmcnt(8)
	v_pk_add_f32 v[50:51], v[50:51], v[216:217]
	v_pk_add_f32 v[48:49], v[48:49], v[214:215]
	v_add_u32_e32 v199, 0xb0000, v198
	global_load_dwordx4 v[202:205], v199, s[44:45] nt
	global_load_dwordx4 v[206:209], v199, s[44:45] offset:64 nt
	global_load_dwordx4 v[210:213], v199, s[44:45] offset:512 nt
	global_load_dwordx4 v[214:217], v199, s[44:45] offset:576 nt
	v_mul_f32_e32 v152, v53, v53
	v_mul_f32_e32 v153, v55, v55
	v_fmac_f32_e32 v56, v148, v148
	v_fmac_f32_e32 v57, v62, v62
	v_fmac_f32_e32 v150, v60, v60
	v_fmac_f32_e32 v151, v58, v58
	v_mul_f32_e32 v154, v49, v49
	v_mul_f32_e32 v155, v51, v51
	v_fmac_f32_e32 v152, v52, v52
	v_fmac_f32_e32 v153, v54, v54
	v_add_f32_e32 v56, v56, v57
	v_add_f32_e32 v57, v150, v151
	v_fmac_f32_e32 v154, v48, v48
	v_fmac_f32_e32 v155, v50, v50
	v_add_f32_e32 v150, v152, v153
	v_add_f32_e32 v56, v56, v57
	v_add_f32_e32 v56, v56, v150
	v_add_f32_e32 v57, v154, v155
	v_add_f32_e32 v56, v56, v57
	ds_bpermute_b32 v57, v171, v56
	s_waitcnt lgkmcnt(0)
	v_add_f32_e32 v56, v56, v57
	ds_bpermute_b32 v57, v172, v56
	s_and_saveexec_b64 s[4:5], vcc
	s_cbranch_execz .LBB0_512
	s_waitcnt lgkmcnt(0)
	v_add_f32_e32 v56, v56, v57
	ds_write_b32 v173, v56 offset:512
.LBB0_512:
	s_or_b64 exec, exec, s[4:5]
	s_mov_b64 s[4:5], 0x90000
	s_waitcnt lgkmcnt(0)
	v_lshl_add_u64 v[56:57], v[132:133], 0, s[4:5]
	v_lshl_add_u64 v[150:151], s[44:45], 0, v[56:57]
	v_lshl_add_u64 v[162:163], v[128:129], 2, v[150:151]
	s_nop 0
	s_waitcnt vmcnt(11)
	v_pk_add_f32 v[46:47], v[46:47], v[220:221]
	v_pk_add_f32 v[150:151], v[44:45], v[218:219]
	s_waitcnt vmcnt(10)
	v_pk_add_f32 v[42:43], v[42:43], v[224:225]
	v_pk_add_f32 v[44:45], v[40:41], v[222:223]
	s_waitcnt vmcnt(9)
	v_pk_add_f32 v[38:39], v[38:39], v[236:237]
	v_pk_add_f32 v[36:37], v[36:37], v[234:235]
	v_mul_f32_e32 v40, v151, v151
	v_mul_f32_e32 v41, v47, v47
	v_mul_f32_e32 v152, v45, v45
	v_mul_f32_e32 v153, v43, v43
	s_waitcnt vmcnt(8)
	v_pk_add_f32 v[34:35], v[34:35], v[240:241]
	v_pk_add_f32 v[32:33], v[32:33], v[238:239]
	v_mul_f32_e32 v154, v37, v37
	v_mul_f32_e32 v155, v39, v39
	v_fmac_f32_e32 v40, v150, v150
	v_fmac_f32_e32 v41, v46, v46
	v_fmac_f32_e32 v152, v44, v44
	v_fmac_f32_e32 v153, v42, v42
	v_mul_f32_e32 v156, v33, v33
	v_mul_f32_e32 v157, v35, v35
	v_fmac_f32_e32 v154, v36, v36
	v_fmac_f32_e32 v155, v38, v38
	v_add_f32_e32 v40, v40, v41
	v_add_f32_e32 v41, v152, v153
	v_fmac_f32_e32 v156, v32, v32
	v_fmac_f32_e32 v157, v34, v34
	v_add_f32_e32 v152, v154, v155
	v_add_f32_e32 v40, v40, v41
	v_add_f32_e32 v40, v40, v152
	v_add_f32_e32 v41, v156, v157
	v_add_f32_e32 v40, v40, v41
	ds_bpermute_b32 v41, v171, v40
	s_waitcnt lgkmcnt(0)
	v_add_f32_e32 v40, v40, v41
	ds_bpermute_b32 v41, v172, v40
	s_and_saveexec_b64 s[4:5], vcc
	s_cbranch_execz .LBB0_514
	s_waitcnt lgkmcnt(0)
	v_add_f32_e32 v40, v40, v41
	ds_write_b32 v173, v40 offset:576
.LBB0_514:
	s_or_b64 exec, exec, s[4:5]
	s_mov_b64 s[4:5], 0xa0000
	s_waitcnt lgkmcnt(0)
	v_lshl_add_u64 v[40:41], v[132:133], 0, s[4:5]
	v_lshl_add_u64 v[152:153], s[44:45], 0, v[40:41]
	v_lshl_add_u64 v[164:165], v[128:129], 2, v[152:153]
	s_nop 0
	s_waitcnt vmcnt(7)
	v_pk_add_f32 v[30:31], v[30:31], v[184:185]
	v_pk_add_f32 v[152:153], v[28:29], v[182:183]
	s_waitcnt vmcnt(6)
	v_pk_add_f32 v[26:27], v[26:27], v[188:189]
	v_pk_add_f32 v[28:29], v[24:25], v[186:187]
	s_waitcnt vmcnt(5)
	v_pk_add_f32 v[22:23], v[22:23], v[192:193]
	v_pk_add_f32 v[20:21], v[20:21], v[190:191]
	v_mul_f32_e32 v24, v153, v153
	v_mul_f32_e32 v25, v31, v31
	v_mul_f32_e32 v154, v29, v29
	v_mul_f32_e32 v155, v27, v27
	s_waitcnt vmcnt(4)
	v_pk_add_f32 v[18:19], v[18:19], v[196:197]
	v_pk_add_f32 v[16:17], v[16:17], v[194:195]
	v_mul_f32_e32 v156, v21, v21
	v_mul_f32_e32 v157, v23, v23
	v_fmac_f32_e32 v24, v152, v152
	v_fmac_f32_e32 v25, v30, v30
	v_fmac_f32_e32 v154, v28, v28
	v_fmac_f32_e32 v155, v26, v26
	v_mul_f32_e32 v158, v17, v17
	v_mul_f32_e32 v159, v19, v19
	v_fmac_f32_e32 v156, v20, v20
	v_fmac_f32_e32 v157, v22, v22
	v_add_f32_e32 v24, v24, v25
	v_add_f32_e32 v25, v154, v155
	v_fmac_f32_e32 v158, v16, v16
	v_fmac_f32_e32 v159, v18, v18
	v_add_f32_e32 v154, v156, v157
	v_add_f32_e32 v24, v24, v25
	v_add_f32_e32 v24, v24, v154
	v_add_f32_e32 v25, v158, v159
	v_add_f32_e32 v24, v24, v25
	ds_bpermute_b32 v25, v171, v24
	s_waitcnt lgkmcnt(0)
	v_add_f32_e32 v24, v24, v25
	ds_bpermute_b32 v25, v172, v24
	s_and_saveexec_b64 s[4:5], vcc
	s_cbranch_execz .LBB0_516
	s_waitcnt lgkmcnt(0)
	v_add_f32_e32 v24, v24, v25
	ds_write_b32 v173, v24 offset:640
.LBB0_516:
	s_or_b64 exec, exec, s[4:5]
	s_mov_b64 s[4:5], 0xb0000
	s_waitcnt lgkmcnt(0)
	v_lshl_add_u64 v[24:25], v[132:133], 0, s[4:5]
	v_lshl_add_u64 v[154:155], s[44:45], 0, v[24:25]
	v_lshl_add_u64 v[162:163], v[128:129], 2, v[154:155]
	s_waitcnt vmcnt(3)
	v_pk_add_f32 v[166:167], v[14:15], v[204:205]
	v_pk_add_f32 v[168:169], v[12:13], v[202:203]
	s_waitcnt vmcnt(2)
	v_pk_add_f32 v[162:163], v[10:11], v[208:209]
	v_pk_add_f32 v[164:165], v[8:9], v[206:207]
	s_waitcnt vmcnt(1)
	v_pk_add_f32 v[158:159], v[6:7], v[212:213]
	v_pk_add_f32 v[160:161], v[4:5], v[210:211]
	s_waitcnt vmcnt(0)
	v_pk_add_f32 v[154:155], v[2:3], v[216:217]
	v_pk_add_f32 v[156:157], v[0:1], v[214:215]
	v_mul_f32_e32 v0, v169, v169
	v_mul_f32_e32 v1, v167, v167
	v_mul_f32_e32 v2, v165, v165
	v_mul_f32_e32 v3, v163, v163
	v_mul_f32_e32 v4, v161, v161
	v_mul_f32_e32 v5, v159, v159
	v_fmac_f32_e32 v0, v168, v168
	v_fmac_f32_e32 v1, v166, v166
	v_fmac_f32_e32 v2, v164, v164
	v_fmac_f32_e32 v3, v162, v162
	v_mul_f32_e32 v6, v157, v157
	v_mul_f32_e32 v7, v155, v155
	v_fmac_f32_e32 v4, v160, v160
	v_fmac_f32_e32 v5, v158, v158
	v_add_f32_e32 v0, v0, v1
	v_add_f32_e32 v1, v2, v3
	v_fmac_f32_e32 v6, v156, v156
	v_fmac_f32_e32 v7, v154, v154
	v_add_f32_e32 v2, v4, v5
	v_add_f32_e32 v0, v0, v1
	v_add_f32_e32 v0, v0, v2
	v_add_f32_e32 v1, v6, v7
	v_add_f32_e32 v0, v0, v1
	ds_bpermute_b32 v1, v171, v0
	s_waitcnt lgkmcnt(0)
	v_add_f32_e32 v0, v0, v1
	ds_bpermute_b32 v1, v172, v0
	s_and_saveexec_b64 s[4:5], vcc
	s_cbranch_execz .LBB0_518
	s_waitcnt lgkmcnt(0)
	v_add_f32_e32 v0, v0, v1
	ds_write_b32 v173, v0 offset:704

.LBB0_530:
	v_lshl_add_u64 v[130:131], v[130:131], 2, s[10:11]
	global_load_dword v182, v[130:131], off sc1
	global_load_dword v183, v[130:131], off offset:64 sc1
	global_load_dword v184, v[130:131], off offset:128 sc1
	global_load_dword v185, v[130:131], off offset:192 sc1
	global_load_dword v186, v[130:131], off offset:512 sc1
	global_load_dword v187, v[130:131], off offset:576 sc1
	global_load_dword v188, v[130:131], off offset:640 sc1
	global_load_dword v189, v[130:131], off offset:704 sc1
	v_mov_b32_e32 v178, 0x3727c5ac
	v_lshl_add_u64 v[132:133], s[66:67], 0, v[132:133]
	v_lshlrev_b64 v[128:129], 2, v[128:129]
	v_lshl_add_u64 v[132:133], v[132:133], 0, v[128:129]
	v_lshl_add_u64 v[136:137], v[136:137], 2, s[10:11]
	s_waitcnt vmcnt(0)
	v_mov_b32_e32 v170, v182
	v_fmamk_f32 v170, v170, 0x3a800000, v178
	v_rsq_f32_e32 v170, v170
	s_nop 0
	v_pk_mul_f32 v[124:125], v[124:125], v[170:171] op_sel_hi:[1,0]
	v_pk_mul_f32 v[126:127], v[126:127], v[170:171] op_sel_hi:[1,0]
	v_pk_mul_f32 v[120:121], v[120:121], v[170:171] op_sel_hi:[1,0]
	v_pk_mul_f32 v[122:123], v[122:123], v[170:171] op_sel_hi:[1,0]
	v_pk_mul_f32 v[172:173], v[116:117], v[170:171] op_sel_hi:[1,0]
	v_pk_mul_f32 v[174:175], v[118:119], v[170:171] op_sel_hi:[1,0]
	v_pk_mul_f32 v[176:177], v[112:113], v[170:171] op_sel_hi:[1,0]
	v_pk_mul_f32 v[170:171], v[114:115], v[170:171] op_sel_hi:[1,0]
	v_pk_mul_f32 v[114:115], v[14:15], v[126:127]
	v_pk_mul_f32 v[112:113], v[12:13], v[124:125]
	v_pk_mul_f32 v[118:119], v[10:11], v[122:123]
	v_pk_mul_f32 v[116:117], v[8:9], v[120:121]
	v_pk_mul_f32 v[122:123], v[6:7], v[174:175]
	v_pk_mul_f32 v[120:121], v[4:5], v[172:173]
	v_pk_mul_f32 v[126:127], v[2:3], v[170:171]
	v_pk_mul_f32 v[124:125], v[0:1], v[176:177]
	global_store_dwordx4 v[132:133], v[112:115], off nt
	global_store_dwordx4 v[132:133], v[116:119], off offset:64 nt
	global_store_dwordx4 v[132:133], v[120:123], off offset:512 nt
	global_store_dwordx4 v[132:133], v[124:127], off offset:576 nt
	v_mov_b32_e32 v112, v183
	v_lshl_add_u64 v[114:115], s[66:67], 0, v[134:135]
	v_lshl_add_u64 v[114:115], v[114:115], 0, v[128:129]
	v_lshl_add_u64 v[116:117], v[140:141], 2, s[10:11]
	v_fmamk_f32 v112, v112, 0x3a800000, v178
	v_rsq_f32_e32 v112, v112
	s_nop 0
	v_pk_mul_f32 v[108:109], v[108:109], v[112:113] op_sel_hi:[1,0]
	v_pk_mul_f32 v[110:111], v[110:111], v[112:113] op_sel_hi:[1,0]
	v_pk_mul_f32 v[104:105], v[104:105], v[112:113] op_sel_hi:[1,0]
	v_pk_mul_f32 v[106:107], v[106:107], v[112:113] op_sel_hi:[1,0]
	v_pk_mul_f32 v[118:119], v[100:101], v[112:113] op_sel_hi:[1,0]
	v_pk_mul_f32 v[120:121], v[102:103], v[112:113] op_sel_hi:[1,0]
	v_pk_mul_f32 v[122:123], v[96:97], v[112:113] op_sel_hi:[1,0]
	v_pk_mul_f32 v[112:113], v[98:99], v[112:113] op_sel_hi:[1,0]
	v_pk_mul_f32 v[98:99], v[14:15], v[110:111]
	v_pk_mul_f32 v[96:97], v[12:13], v[108:109]
	v_pk_mul_f32 v[102:103], v[10:11], v[106:107]
	v_pk_mul_f32 v[100:101], v[8:9], v[104:105]
	v_pk_mul_f32 v[106:107], v[6:7], v[120:121]
	v_pk_mul_f32 v[104:105], v[4:5], v[118:119]
	v_pk_mul_f32 v[110:111], v[2:3], v[112:113]
	v_pk_mul_f32 v[108:109], v[0:1], v[122:123]
	global_store_dwordx4 v[114:115], v[96:99], off nt
	global_store_dwordx4 v[114:115], v[100:103], off offset:64 nt
	global_store_dwordx4 v[114:115], v[104:107], off offset:512 nt
	global_store_dwordx4 v[114:115], v[108:111], off offset:576 nt
	v_mov_b32_e32 v96, v184
	v_lshl_add_u64 v[98:99], s[66:67], 0, v[138:139]
	v_lshl_add_u64 v[98:99], v[98:99], 0, v[128:129]
	v_lshl_add_u64 v[100:101], v[144:145], 2, s[10:11]
	v_fmamk_f32 v96, v96, 0x3a800000, v178
	v_rsq_f32_e32 v96, v96
	s_nop 0
	v_pk_mul_f32 v[92:93], v[92:93], v[96:97] op_sel_hi:[1,0]
	v_pk_mul_f32 v[94:95], v[94:95], v[96:97] op_sel_hi:[1,0]
	v_pk_mul_f32 v[88:89], v[88:89], v[96:97] op_sel_hi:[1,0]
	v_pk_mul_f32 v[90:91], v[90:91], v[96:97] op_sel_hi:[1,0]
	v_pk_mul_f32 v[102:103], v[84:85], v[96:97] op_sel_hi:[1,0]
	v_pk_mul_f32 v[104:105], v[86:87], v[96:97] op_sel_hi:[1,0]
	v_pk_mul_f32 v[106:107], v[80:81], v[96:97] op_sel_hi:[1,0]
	v_pk_mul_f32 v[96:97], v[82:83], v[96:97] op_sel_hi:[1,0]
	v_pk_mul_f32 v[82:83], v[14:15], v[94:95]
	v_pk_mul_f32 v[80:81], v[12:13], v[92:93]
	v_pk_mul_f32 v[86:87], v[10:11], v[90:91]
	v_pk_mul_f32 v[84:85], v[8:9], v[88:89]
	v_pk_mul_f32 v[90:91], v[6:7], v[104:105]
	v_pk_mul_f32 v[88:89], v[4:5], v[102:103]
	v_pk_mul_f32 v[94:95], v[2:3], v[96:97]
	v_pk_mul_f32 v[92:93], v[0:1], v[106:107]
	global_store_dwordx4 v[98:99], v[80:83], off nt
	global_store_dwordx4 v[98:99], v[84:87], off offset:64 nt
	global_store_dwordx4 v[98:99], v[88:91], off offset:512 nt
	global_store_dwordx4 v[98:99], v[92:95], off offset:576 nt
	v_mov_b32_e32 v80, v185
	v_lshl_add_u64 v[82:83], s[66:67], 0, v[142:143]
	v_lshl_add_u64 v[82:83], v[82:83], 0, v[128:129]
	v_fmamk_f32 v80, v80, 0x3a800000, v178
	v_rsq_f32_e32 v80, v80
	s_nop 0
	v_pk_mul_f32 v[84:85], v[146:147], v[80:81] op_sel_hi:[1,0]
	v_pk_mul_f32 v[78:79], v[78:79], v[80:81] op_sel_hi:[1,0]
	v_pk_mul_f32 v[76:77], v[76:77], v[80:81] op_sel_hi:[1,0]
	v_pk_mul_f32 v[74:75], v[74:75], v[80:81] op_sel_hi:[1,0]
	v_pk_mul_f32 v[86:87], v[68:69], v[80:81] op_sel_hi:[1,0]
	v_pk_mul_f32 v[88:89], v[70:71], v[80:81] op_sel_hi:[1,0]
	v_pk_mul_f32 v[90:91], v[64:65], v[80:81] op_sel_hi:[1,0]
	v_pk_mul_f32 v[80:81], v[66:67], v[80:81] op_sel_hi:[1,0]
	v_pk_mul_f32 v[66:67], v[14:15], v[78:79]
	v_pk_mul_f32 v[64:65], v[12:13], v[84:85]
	v_pk_mul_f32 v[70:71], v[10:11], v[74:75]
	v_pk_mul_f32 v[68:69], v[8:9], v[76:77]
	v_pk_mul_f32 v[76:77], v[6:7], v[88:89]
	v_pk_mul_f32 v[74:75], v[4:5], v[86:87]
	v_pk_mul_f32 v[80:81], v[2:3], v[80:81]
	v_pk_mul_f32 v[78:79], v[0:1], v[90:91]
	global_store_dwordx4 v[82:83], v[64:67], off nt
	global_store_dwordx4 v[82:83], v[68:71], off offset:64 nt
	global_store_dwordx4 v[82:83], v[74:77], off offset:512 nt
	global_store_dwordx4 v[82:83], v[78:81], off offset:576 nt
	v_mov_b32_e32 v64, v186
	v_lshl_add_u64 v[66:67], s[66:67], 0, v[72:73]
	v_lshl_add_u64 v[66:67], v[66:67], 0, v[128:129]
	v_fmamk_f32 v64, v64, 0x3a800000, v178
	v_rsq_f32_e32 v64, v64
	s_nop 0
	v_pk_mul_f32 v[68:69], v[148:149], v[64:65] op_sel_hi:[1,0]
	v_pk_mul_f32 v[62:63], v[62:63], v[64:65] op_sel_hi:[1,0]
	v_pk_mul_f32 v[60:61], v[60:61], v[64:65] op_sel_hi:[1,0]
	v_pk_mul_f32 v[58:59], v[58:59], v[64:65] op_sel_hi:[1,0]
	v_pk_mul_f32 v[70:71], v[52:53], v[64:65] op_sel_hi:[1,0]
	v_pk_mul_f32 v[72:73], v[54:55], v[64:65] op_sel_hi:[1,0]
	v_pk_mul_f32 v[74:75], v[48:49], v[64:65] op_sel_hi:[1,0]
	v_pk_mul_f32 v[64:65], v[50:51], v[64:65] op_sel_hi:[1,0]
	v_pk_mul_f32 v[50:51], v[14:15], v[62:63]
	v_pk_mul_f32 v[48:49], v[12:13], v[68:69]
	v_pk_mul_f32 v[54:55], v[10:11], v[58:59]
	v_pk_mul_f32 v[52:53], v[8:9], v[60:61]
	v_pk_mul_f32 v[60:61], v[6:7], v[72:73]
	v_pk_mul_f32 v[58:59], v[4:5], v[70:71]
	v_pk_mul_f32 v[64:65], v[2:3], v[64:65]
	v_pk_mul_f32 v[62:63], v[0:1], v[74:75]
	global_store_dwordx4 v[66:67], v[48:51], off nt
	global_store_dwordx4 v[66:67], v[52:55], off offset:64 nt
	global_store_dwordx4 v[66:67], v[58:61], off offset:512 nt
	global_store_dwordx4 v[66:67], v[62:65], off offset:576 nt
	v_mov_b32_e32 v48, v187
	v_lshl_add_u64 v[50:51], s[66:67], 0, v[56:57]
	v_lshl_add_u64 v[50:51], v[50:51], 0, v[128:129]
	v_fmamk_f32 v48, v48, 0x3a800000, v178
	v_rsq_f32_e32 v48, v48
	s_nop 0
	v_pk_mul_f32 v[52:53], v[150:151], v[48:49] op_sel_hi:[1,0]
	v_pk_mul_f32 v[46:47], v[46:47], v[48:49] op_sel_hi:[1,0]
	v_pk_mul_f32 v[44:45], v[44:45], v[48:49] op_sel_hi:[1,0]
	v_pk_mul_f32 v[42:43], v[42:43], v[48:49] op_sel_hi:[1,0]
	v_pk_mul_f32 v[54:55], v[36:37], v[48:49] op_sel_hi:[1,0]
	v_pk_mul_f32 v[56:57], v[38:39], v[48:49] op_sel_hi:[1,0]
	v_pk_mul_f32 v[58:59], v[32:33], v[48:49] op_sel_hi:[1,0]
	v_pk_mul_f32 v[48:49], v[34:35], v[48:49] op_sel_hi:[1,0]
	v_pk_mul_f32 v[34:35], v[14:15], v[46:47]
	v_pk_mul_f32 v[32:33], v[12:13], v[52:53]
	v_pk_mul_f32 v[38:39], v[10:11], v[42:43]
	v_pk_mul_f32 v[36:37], v[8:9], v[44:45]
	v_pk_mul_f32 v[44:45], v[6:7], v[56:57]
	v_pk_mul_f32 v[42:43], v[4:5], v[54:55]
	v_pk_mul_f32 v[48:49], v[2:3], v[48:49]
	v_pk_mul_f32 v[46:47], v[0:1], v[58:59]
	global_store_dwordx4 v[50:51], v[32:35], off nt
	global_store_dwordx4 v[50:51], v[36:39], off offset:64 nt
	global_store_dwordx4 v[50:51], v[42:45], off offset:512 nt
	global_store_dwordx4 v[50:51], v[46:49], off offset:576 nt
	v_mov_b32_e32 v32, v188
	v_lshl_add_u64 v[34:35], s[66:67], 0, v[40:41]
	v_lshl_add_u64 v[34:35], v[34:35], 0, v[128:129]
	v_fmamk_f32 v32, v32, 0x3a800000, v178
	v_rsq_f32_e32 v32, v32
	s_nop 0
	v_pk_mul_f32 v[36:37], v[152:153], v[32:33] op_sel_hi:[1,0]
	v_pk_mul_f32 v[30:31], v[30:31], v[32:33] op_sel_hi:[1,0]
	v_pk_mul_f32 v[28:29], v[28:29], v[32:33] op_sel_hi:[1,0]
	v_pk_mul_f32 v[26:27], v[26:27], v[32:33] op_sel_hi:[1,0]
	v_pk_mul_f32 v[38:39], v[20:21], v[32:33] op_sel_hi:[1,0]
	v_pk_mul_f32 v[40:41], v[22:23], v[32:33] op_sel_hi:[1,0]
	v_pk_mul_f32 v[42:43], v[16:17], v[32:33] op_sel_hi:[1,0]
	v_pk_mul_f32 v[32:33], v[18:19], v[32:33] op_sel_hi:[1,0]
	v_pk_mul_f32 v[18:19], v[14:15], v[30:31]
	v_pk_mul_f32 v[16:17], v[12:13], v[36:37]
	v_pk_mul_f32 v[22:23], v[10:11], v[26:27]
	v_pk_mul_f32 v[20:21], v[8:9], v[28:29]
	v_pk_mul_f32 v[28:29], v[6:7], v[40:41]
	v_pk_mul_f32 v[26:27], v[4:5], v[38:39]
	v_pk_mul_f32 v[32:33], v[2:3], v[32:33]
	v_pk_mul_f32 v[30:31], v[0:1], v[42:43]
	global_store_dwordx4 v[34:35], v[16:19], off nt
	global_store_dwordx4 v[34:35], v[20:23], off offset:64 nt
	global_store_dwordx4 v[34:35], v[26:29], off offset:512 nt
	global_store_dwordx4 v[34:35], v[30:33], off offset:576 nt
	v_mov_b32_e32 v16, v189
	v_lshl_add_u64 v[18:19], s[66:67], 0, v[24:25]
	v_lshl_add_u64 v[18:19], v[18:19], 0, v[128:129]
	v_fmac_f32_e32 v178, 0x3a800000, v16
	v_rsq_f32_e32 v16, v178
	s_nop 0
	v_pk_mul_f32 v[20:21], v[168:169], v[16:17] op_sel_hi:[1,0]
	v_pk_mul_f32 v[22:23], v[166:167], v[16:17] op_sel_hi:[1,0]
	v_pk_mul_f32 v[24:25], v[164:165], v[16:17] op_sel_hi:[1,0]
	v_pk_mul_f32 v[26:27], v[162:163], v[16:17] op_sel_hi:[1,0]
	v_pk_mul_f32 v[28:29], v[160:161], v[16:17] op_sel_hi:[1,0]
	v_pk_mul_f32 v[30:31], v[158:159], v[16:17] op_sel_hi:[1,0]
	v_pk_mul_f32 v[32:33], v[156:157], v[16:17] op_sel_hi:[1,0]
	v_pk_mul_f32 v[16:17], v[154:155], v[16:17] op_sel_hi:[1,0]
	v_pk_mul_f32 v[14:15], v[14:15], v[22:23]
	v_pk_mul_f32 v[12:13], v[12:13], v[20:21]
	v_pk_mul_f32 v[10:11], v[10:11], v[26:27]
	v_pk_mul_f32 v[8:9], v[8:9], v[24:25]
	v_pk_mul_f32 v[6:7], v[6:7], v[30:31]
	v_pk_mul_f32 v[4:5], v[4:5], v[28:29]
	v_pk_mul_f32 v[2:3], v[2:3], v[16:17]
	v_pk_mul_f32 v[0:1], v[0:1], v[32:33]
	global_store_dwordx4 v[18:19], v[12:15], off nt
	global_store_dwordx4 v[18:19], v[8:11], off offset:64 nt
	global_store_dwordx4 v[18:19], v[4:7], off offset:512 nt
	global_store_dwordx4 v[18:19], v[0:3], off offset:576 nt
	s_bfe_u32 s0, s79, 0x20006
	s_cmp_lg_u32 s0, 0
	s_cbranch_scc1 .Ls3_done
	s_lshl_b32 s0, s72, 8
	s_add_u32 s0, s68, s0
	s_addc_u32 s1, s69, 0
	v_mov_b32_e32 v9, 0x48000
	s_mov_b32 s3, 0x100000
.Ls3_spin:
	global_load_dword v13, v9, s[0:1] sc1
	s_waitcnt vmcnt(0)
	v_readfirstlane_b32 s80, v13
	s_nop 3
	s_cmp_ge_u32 s80, 64
	s_cbranch_scc1 .Ls3_go
	s_sleep 1
	s_sub_u32 s3, s3, 1
	s_cmp_eq_u32 s3, 0
	s_cbranch_scc0 .Ls3_spin
.Ls3_go:
	v_add_u32_e32 v13, 0x20400, v252
	global_load_dword v12, v13, s[68:69] sc1
	v_mov_b32_e32 v14, 0x3727c5ac
	v_mov_b32_e32 v9, 0
	v_mov_b32_e32 v11, 0
	v_mov_b32_e32 v8, v250
	v_mov_b32_e32 v10, v251
	v_mov_b32_e32 v0, v242
	v_mov_b32_e32 v1, v243
	v_mov_b32_e32 v2, v244
	v_mov_b32_e32 v3, v245
	v_mov_b32_e32 v4, v246
	v_mov_b32_e32 v5, v247
	v_mov_b32_e32 v6, v248
	v_mov_b32_e32 v7, v249
	v_lshl_add_u64 v[8:9], s[66:67], 0, v[8:9]
	v_lshl_add_u64 v[8:9], v[10:11], 2, v[8:9]
	v_add_co_u32_e32 v8, vcc, 0x4000000, v8
	s_waitcnt vmcnt(0)
	v_fmac_f32_e32 v14, 0x3a800000, v12
	v_rsq_f32_e32 v12, v14
	v_addc_co_u32_e32 v9, vcc, 0, v9, vcc
	v_pk_mul_f32 v[6:7], v[6:7], v[12:13] op_sel_hi:[1,0]
	v_pk_mul_f32 v[4:5], v[4:5], v[12:13] op_sel_hi:[1,0]
	v_pk_mul_f32 v[0:1], v[0:1], v[6:7]
	v_pk_mul_f32 v[2:3], v[2:3], v[4:5]
	global_store_dwordx4 v[8:9], v[0:3], off
.Ls3_done:
	s_branch .LBB0_563
.LBB0_531:
	s_mov_b64 s[0:1], -1
	s_and_b64 vcc, exec, s[8:9]
	s_cbranch_vccz .LBB0_540
	s_mul_i32 s0, s90, s86
	s_add_i32 s3, s0, s2
	s_cmpk_gt_i32 s3, 0x1ff
	s_cbranch_scc1 .LBB0_539
	v_mbcnt_lo_u32_b32 v0, -1, 0
	v_mbcnt_hi_u32_b32 v0, -1, v0
	v_and_b32_e32 v2, 64, v0
	s_waitcnt lgkmcnt(0)
	v_xor_b32_e32 v1, 16, v0
	v_add_u32_e32 v2, 64, v2
	v_cmp_lt_i32_e32 vcc, v1, v2
	s_add_u32 s4, s68, 0x20400
	s_waitcnt vmcnt(0)
	v_and_b32_e32 v8, 48, v201
	v_cndmask_b32_e32 v1, v0, v1, vcc
	v_lshlrev_b32_e32 v17, 2, v1
	v_xor_b32_e32 v1, 32, v0
	v_cmp_lt_i32_e32 vcc, v1, v2
	v_mov_b32_e32 v9, 0
	v_lshlrev_b32_e32 v16, 2, v232
	v_cndmask_b32_e32 v0, v0, v1, vcc
	v_lshlrev_b32_e32 v18, 2, v0
	v_cmp_gt_u32_e64 s[0:1], 16, v200
	s_addc_u32 s5, s69, 0
	v_lshlrev_b32_e32 v19, 11, v233
	s_lshl_b32 s14, s3, 4
	s_lshl_b32 s15, s86, 7
	v_lshl_add_u64 v[10:11], s[68:69], 0, v[8:9]
	s_lshl_b32 s16, s3, 1
	s_lshl_b32 s17, s86, 4
	s_mov_b64 s[8:9], 0x400
	s_branch .LBB0_535
